# G4 SwiGLU epilogue software-pipelined across row groups: transcendentals of group g interleaved 1:1 with the plain multiplies of group g+1
# baseline (speedup 1.0000x reference)
; __device__ __forceinline__ unsigned cvt_pk_bf16(float lo, float hi) { unsigned r; asm volatile("v_cvt_pk_bf16_f32 %0, %1, %2" : "=v"(r) : "v"(lo), "v"(hi)); return r; }
; #define LAS __attribute__((address_space(3)))
; __device__ __forceinline__ float sigmoid_f(float x) { return __builtin_amdgcn_rcpf(1.0f + __builtin_amdgcn_exp2f(-1.4426950408889634f * x)); }
; __device__ __forceinline__ float rstd4(const f32x4 q) { return __builtin_amdgcn_rsqf(((q[0] + q[1]) + (q[2] + q[3])) * (1.0f / DM) + EPS); }
;     __device__ __forceinline__ void operator()(const f32x4 (&acc)[2][2][4][2], const pg8::Unit& u, int wr, int wc, int fr, int fq, LAS unsigned char* lds, int wid, int lane, const pg8::Unit& nxt, bool has_next, int ui) const {
;     ...
; #pragma unroll
;         for (int ai = 0; ai < 2; ++ai) {
; #pragma unroll
;             for (int m = 0; m < 4; ++m) {
;                 const int row = row0 + ai * 128 + m * 16; const float r_ = R[wr * 64 + fr + ai * 128 + m * 16];
;                 const f32x4 g0 = acc[ai][0][m][0] * r_, g1 = acc[ai][0][m][1] * r_, u0 = acc[ai][1][m][0] * r_, u1 = acc[ai][1][m][1] * r_;
;                 v4u w;
;                 w.x = cvt_pk_bf16(g0[0] * sigmoid_f(g0[0]) * u0[0], g0[1] * sigmoid_f(g0[1]) * u0[1]); w.y = cvt_pk_bf16(g0[2] * sigmoid_f(g0[2]) * u0[2], g0[3] * sigmoid_f(g0[3]) * u0[3]);
;                 w.z = cvt_pk_bf16(g1[0] * sigmoid_f(g1[0]) * u1[0], g1[1] * sigmoid_f(g1[1]) * u1[1]); w.w = cvt_pk_bf16(g1[2] * sigmoid_f(g1[2]) * u1[2], g1[3] * sigmoid_f(g1[3]) * u1[3]);
;                 *(v4u*)(ACT + (size_t)row * FF + col) = w;
;             }
;             if (ai == 0) {
;                 __builtin_amdgcn_sched_barrier(0);
;                 float rn = rstd4(qn); asm volatile("" : "+v"(rn));
;                 if (pre) ((LAS float*)(lds + RS_OFF))[((ui + 1) & 1) * 256 + tid] = rn;
;                 __builtin_amdgcn_sched_barrier(0);
;             }
.LBB0_586:
	s_or_b64 exec, exec, s[22:23]
	s_lshl_b32 s11, s82, 8
	s_and_b32 s11, s11, 0x100
	v_lshl_add_u32 v155, s11, 2, v151
	ds_read_b32 v227, v155
	ds_read_b32 v232, v155 offset:64
	ds_read_b32 v237, v155 offset:128
	ds_read_b32 v238, v155 offset:192
	ds_read_b32 v239, v155 offset:512
	ds_read_b32 v240, v155 offset:576
	ds_read_b32 v241, v155 offset:640
	ds_read_b32 v242, v155 offset:704
	v_lshl_or_b32 v148, s12, 7, v153
	v_lshl_add_u32 v236, s13, 8, v1
	v_ashrrev_i32_e32 v149, 31, v148
	v_lshlrev_b64 v[224:225], 1, v[148:149]
	v_lshl_add_u64 v[224:225], v[224:225], 0, s[40:41]
	s_waitcnt lgkmcnt(0)
	v_mul_f32_e32 v230, 0xbfb8aa3b, v227
	v_mul_f32_e32 v231, v227, v227
	v_rcp_f32_e32 v231, v231
	v_mul_f32_e32 v122, v130, v122
	v_mul_f32_e32 v123, v131, v123
	v_mul_f32_e32 v124, v132, v124
	v_mul_f32_e32 v125, v133, v125
	v_mul_f32_e32 v118, v126, v118
	v_mul_f32_e32 v119, v127, v119
	v_mul_f32_e32 v120, v128, v120
	v_mul_f32_e32 v121, v129, v121
	v_mul_f32_e32 v130, v230, v130
	v_mul_f32_e32 v131, v230, v131
	v_mul_f32_e32 v132, v230, v132
	v_mul_f32_e32 v133, v230, v133
	v_mul_f32_e32 v126, v230, v126
	v_mul_f32_e32 v127, v230, v127
	v_mul_f32_e32 v128, v230, v128
	v_mul_f32_e32 v129, v230, v129
	v_mul_f32_e32 v230, 0xbfb8aa3b, v232
	v_mul_f32_e32 v243, v232, v232
	v_rcp_f32_e32 v243, v243
	v_exp_f32_e32 v130, v130
	v_mul_f32_e32 v106, v114, v106
	v_exp_f32_e32 v131, v131
	v_mul_f32_e32 v107, v115, v107
	v_exp_f32_e32 v132, v132
	v_mul_f32_e32 v108, v116, v108
	v_exp_f32_e32 v133, v133
	v_mul_f32_e32 v109, v117, v109
	v_exp_f32_e32 v126, v126
	v_mul_f32_e32 v102, v110, v102
	v_exp_f32_e32 v127, v127
	v_mul_f32_e32 v103, v111, v103
	v_exp_f32_e32 v128, v128
	v_mul_f32_e32 v104, v112, v104
	v_exp_f32_e32 v129, v129
	v_mul_f32_e32 v105, v113, v105
	v_fma_f32 v130, v130, v231, v231
	v_mul_f32_e32 v114, v230, v114
	v_fma_f32 v131, v131, v231, v231
	v_rcp_f32_e32 v130, v130
	v_mul_f32_e32 v115, v230, v115
	v_fma_f32 v132, v132, v231, v231
	v_rcp_f32_e32 v131, v131
	v_mul_f32_e32 v116, v230, v116
	v_fma_f32 v133, v133, v231, v231
	v_rcp_f32_e32 v132, v132
	v_mul_f32_e32 v117, v230, v117
	v_fma_f32 v126, v126, v231, v231
	v_rcp_f32_e32 v133, v133
	v_mul_f32_e32 v110, v230, v110
	v_fma_f32 v127, v127, v231, v231
	v_rcp_f32_e32 v126, v126
	v_mul_f32_e32 v111, v230, v111
	v_fma_f32 v128, v128, v231, v231
	v_rcp_f32_e32 v127, v127
	v_mul_f32_e32 v112, v230, v112
	v_fma_f32 v129, v129, v231, v231
	v_rcp_f32_e32 v128, v128
	v_mul_f32_e32 v113, v230, v113
	v_rcp_f32_e32 v129, v129
	v_mul_f32_e32 v122, v122, v130
	v_mul_f32_e32 v123, v123, v131
	v_mul_f32_e32 v124, v124, v132
	v_mul_f32_e32 v125, v125, v133
	v_mul_f32_e32 v118, v118, v126
	v_mul_f32_e32 v119, v119, v127
	v_mul_f32_e32 v120, v120, v128
	v_mul_f32_e32 v121, v121, v129
	v_cvt_pk_bf16_f32 v122, v122, v123
	v_cvt_pk_bf16_f32 v123, v124, v125
	v_cvt_pk_bf16_f32 v124, v118, v119
	v_cvt_pk_bf16_f32 v125, v120, v121
	v_mov_b32_e32 v226, v236
	v_mad_i64_i32 v[228:229], s[12:13], v226, s55, v[224:225]
	global_store_dwordx4 v[228:229], v[122:125], off
	v_mul_f32_e32 v230, 0xbfb8aa3b, v237
	v_mul_f32_e32 v231, v237, v237
	v_rcp_f32_e32 v231, v231
	v_exp_f32_e32 v114, v114
	v_mul_f32_e32 v86, v94, v86
	v_exp_f32_e32 v115, v115
	v_mul_f32_e32 v87, v95, v87
	v_exp_f32_e32 v116, v116
	v_mul_f32_e32 v88, v96, v88
	v_exp_f32_e32 v117, v117
	v_mul_f32_e32 v89, v97, v89
	v_exp_f32_e32 v110, v110
	v_mul_f32_e32 v82, v90, v82
	v_exp_f32_e32 v111, v111
	v_mul_f32_e32 v83, v91, v83
	v_exp_f32_e32 v112, v112
	v_mul_f32_e32 v84, v92, v84
	v_exp_f32_e32 v113, v113
	v_mul_f32_e32 v85, v93, v85
	v_fma_f32 v114, v114, v243, v243
	v_mul_f32_e32 v94, v230, v94
	v_fma_f32 v115, v115, v243, v243
	v_rcp_f32_e32 v114, v114
	v_mul_f32_e32 v95, v230, v95
	v_fma_f32 v116, v116, v243, v243
	v_rcp_f32_e32 v115, v115
	v_mul_f32_e32 v96, v230, v96
	v_fma_f32 v117, v117, v243, v243
	v_rcp_f32_e32 v116, v116
	v_mul_f32_e32 v97, v230, v97
	v_fma_f32 v110, v110, v243, v243
	v_rcp_f32_e32 v117, v117
	v_mul_f32_e32 v90, v230, v90
	v_fma_f32 v111, v111, v243, v243
	v_rcp_f32_e32 v110, v110
	v_mul_f32_e32 v91, v230, v91
	v_fma_f32 v112, v112, v243, v243
	v_rcp_f32_e32 v111, v111
	v_mul_f32_e32 v92, v230, v92
	v_fma_f32 v113, v113, v243, v243
	v_rcp_f32_e32 v112, v112
	v_mul_f32_e32 v93, v230, v93
	v_rcp_f32_e32 v113, v113
	v_mul_f32_e32 v106, v106, v114
	v_mul_f32_e32 v107, v107, v115
	v_mul_f32_e32 v108, v108, v116
	v_mul_f32_e32 v109, v109, v117
	v_mul_f32_e32 v102, v102, v110
	v_mul_f32_e32 v103, v103, v111
	v_mul_f32_e32 v104, v104, v112
	v_mul_f32_e32 v105, v105, v113
	v_cvt_pk_bf16_f32 v106, v106, v107
	v_cvt_pk_bf16_f32 v107, v108, v109
	v_cvt_pk_bf16_f32 v108, v102, v103
	v_cvt_pk_bf16_f32 v109, v104, v105
	v_or_b32_e32 v226, 16, v236
	v_mad_i64_i32 v[228:229], s[12:13], v226, s55, v[224:225]
	global_store_dwordx4 v[228:229], v[106:109], off
	v_mul_f32_e32 v230, 0xbfb8aa3b, v238
	v_mul_f32_e32 v243, v238, v238
	v_rcp_f32_e32 v243, v243
	v_exp_f32_e32 v94, v94
	v_mul_f32_e32 v70, v78, v70
	v_exp_f32_e32 v95, v95
	v_mul_f32_e32 v71, v79, v71
	v_exp_f32_e32 v96, v96
	v_mul_f32_e32 v72, v80, v72
	v_exp_f32_e32 v97, v97
	v_mul_f32_e32 v73, v81, v73
	v_exp_f32_e32 v90, v90
	v_mul_f32_e32 v66, v74, v66
	v_exp_f32_e32 v91, v91
	v_mul_f32_e32 v67, v75, v67
	v_exp_f32_e32 v92, v92
	v_mul_f32_e32 v68, v76, v68
	v_exp_f32_e32 v93, v93
	v_mul_f32_e32 v69, v77, v69
	v_fma_f32 v94, v94, v231, v231
	v_mul_f32_e32 v78, v230, v78
	v_fma_f32 v95, v95, v231, v231
	v_rcp_f32_e32 v94, v94
	v_mul_f32_e32 v79, v230, v79
	v_fma_f32 v96, v96, v231, v231
	v_rcp_f32_e32 v95, v95
	v_mul_f32_e32 v80, v230, v80
	v_fma_f32 v97, v97, v231, v231
; __device__ __forceinline__ unsigned cvt_pk_bf16(float lo, float hi) { unsigned r; asm volatile("v_cvt_pk_bf16_f32 %0, %1, %2" : "=v"(r) : "v"(lo), "v"(hi)); return r; }
; #define LAS __attribute__((address_space(3)))
; __device__ __forceinline__ float sigmoid_f(float x) { return __builtin_amdgcn_rcpf(1.0f + __builtin_amdgcn_exp2f(-1.4426950408889634f * x)); }
; __device__ __forceinline__ float rstd4(const f32x4 q) { return __builtin_amdgcn_rsqf(((q[0] + q[1]) + (q[2] + q[3])) * (1.0f / DM) + EPS); }
;     __device__ __forceinline__ void operator()(const f32x4 (&acc)[2][2][4][2], const pg8::Unit& u, int wr, int wc, int fr, int fq, LAS unsigned char* lds, int wid, int lane, const pg8::Unit& nxt, bool has_next, int ui) const {
;     ...
; #pragma unroll
;         for (int ai = 0; ai < 2; ++ai) {
; #pragma unroll
;             for (int m = 0; m < 4; ++m) {
;                 const int row = row0 + ai * 128 + m * 16; const float r_ = R[wr * 64 + fr + ai * 128 + m * 16];
;                 const f32x4 g0 = acc[ai][0][m][0] * r_, g1 = acc[ai][0][m][1] * r_, u0 = acc[ai][1][m][0] * r_, u1 = acc[ai][1][m][1] * r_;
;                 v4u w;
;                 w.x = cvt_pk_bf16(g0[0] * sigmoid_f(g0[0]) * u0[0], g0[1] * sigmoid_f(g0[1]) * u0[1]); w.y = cvt_pk_bf16(g0[2] * sigmoid_f(g0[2]) * u0[2], g0[3] * sigmoid_f(g0[3]) * u0[3]);
;                 w.z = cvt_pk_bf16(g1[0] * sigmoid_f(g1[0]) * u1[0], g1[1] * sigmoid_f(g1[1]) * u1[1]); w.w = cvt_pk_bf16(g1[2] * sigmoid_f(g1[2]) * u1[2], g1[3] * sigmoid_f(g1[3]) * u1[3]);
;                 *(v4u*)(ACT + (size_t)row * FF + col) = w;
;             }
;             if (ai == 0) {
;                 __builtin_amdgcn_sched_barrier(0);
;                 float rn = rstd4(qn); asm volatile("" : "+v"(rn));
;                 if (pre) ((LAS float*)(lds + RS_OFF))[((ui + 1) & 1) * 256 + tid] = rn;
;                 __builtin_amdgcn_sched_barrier(0);
;             }
	v_rcp_f32_e32 v96, v96
	v_mul_f32_e32 v81, v230, v81
	v_fma_f32 v90, v90, v231, v231
	v_rcp_f32_e32 v97, v97
	v_mul_f32_e32 v74, v230, v74
	v_fma_f32 v91, v91, v231, v231
	v_rcp_f32_e32 v90, v90
	v_mul_f32_e32 v75, v230, v75
	v_fma_f32 v92, v92, v231, v231
	v_rcp_f32_e32 v91, v91
	v_mul_f32_e32 v76, v230, v76
	v_fma_f32 v93, v93, v231, v231
	v_rcp_f32_e32 v92, v92
	v_mul_f32_e32 v77, v230, v77
	v_rcp_f32_e32 v93, v93
	v_mul_f32_e32 v86, v86, v94
	v_mul_f32_e32 v87, v87, v95
	v_mul_f32_e32 v88, v88, v96
	v_mul_f32_e32 v89, v89, v97
	v_mul_f32_e32 v82, v82, v90
	v_mul_f32_e32 v83, v83, v91
	v_mul_f32_e32 v84, v84, v92
	v_mul_f32_e32 v85, v85, v93
	v_cvt_pk_bf16_f32 v86, v86, v87
	v_cvt_pk_bf16_f32 v87, v88, v89
	v_cvt_pk_bf16_f32 v88, v82, v83
	v_cvt_pk_bf16_f32 v89, v84, v85
	v_or_b32_e32 v226, 32, v236
	v_mad_i64_i32 v[228:229], s[12:13], v226, s55, v[224:225]
	global_store_dwordx4 v[228:229], v[86:89], off
	v_mul_f32_e32 v230, 0xbfb8aa3b, v239
	v_mul_f32_e32 v231, v239, v239
	v_rcp_f32_e32 v231, v231
	v_exp_f32_e32 v78, v78
	v_mul_f32_e32 v54, v62, v54
	v_exp_f32_e32 v79, v79
	v_mul_f32_e32 v55, v63, v55
	v_exp_f32_e32 v80, v80
	v_mul_f32_e32 v56, v64, v56
	v_exp_f32_e32 v81, v81
	v_mul_f32_e32 v57, v65, v57
	v_exp_f32_e32 v74, v74
	v_mul_f32_e32 v50, v58, v50
	v_exp_f32_e32 v75, v75
	v_mul_f32_e32 v51, v59, v51
	v_exp_f32_e32 v76, v76
	v_mul_f32_e32 v52, v60, v52
	v_exp_f32_e32 v77, v77
	v_mul_f32_e32 v53, v61, v53
	v_fma_f32 v78, v78, v243, v243
	v_mul_f32_e32 v62, v230, v62
	v_fma_f32 v79, v79, v243, v243
	v_rcp_f32_e32 v78, v78
	v_mul_f32_e32 v63, v230, v63
	v_fma_f32 v80, v80, v243, v243
	v_rcp_f32_e32 v79, v79
	v_mul_f32_e32 v64, v230, v64
	v_fma_f32 v81, v81, v243, v243
	v_rcp_f32_e32 v80, v80
	v_mul_f32_e32 v65, v230, v65
	v_fma_f32 v74, v74, v243, v243
	v_rcp_f32_e32 v81, v81
	v_mul_f32_e32 v58, v230, v58
	v_fma_f32 v75, v75, v243, v243
	v_rcp_f32_e32 v74, v74
	v_mul_f32_e32 v59, v230, v59
	v_fma_f32 v76, v76, v243, v243
	v_rcp_f32_e32 v75, v75
	v_mul_f32_e32 v60, v230, v60
	v_fma_f32 v77, v77, v243, v243
	v_rcp_f32_e32 v76, v76
	v_mul_f32_e32 v61, v230, v61
	v_rcp_f32_e32 v77, v77
	v_mul_f32_e32 v70, v70, v78
	v_mul_f32_e32 v71, v71, v79
	v_mul_f32_e32 v72, v72, v80
	v_mul_f32_e32 v73, v73, v81
	v_mul_f32_e32 v66, v66, v74
	v_mul_f32_e32 v67, v67, v75
	v_mul_f32_e32 v68, v68, v76
	v_mul_f32_e32 v69, v69, v77
	v_cvt_pk_bf16_f32 v70, v70, v71
	v_cvt_pk_bf16_f32 v71, v72, v73
	v_cvt_pk_bf16_f32 v72, v66, v67
	v_cvt_pk_bf16_f32 v73, v68, v69
	v_or_b32_e32 v226, 48, v236
	v_mad_i64_i32 v[228:229], s[12:13], v226, s55, v[224:225]
	global_store_dwordx4 v[228:229], v[70:73], off
	s_waitcnt vmcnt(4)
	s_nop 0
	v_add_f32_e32 v233, v98, v99
	v_add_f32_e32 v226, v100, v101
	v_add_f32_e32 v233, v233, v226
	v_fmamk_f32 v233, v233, 0x3a800000, v245
	v_rsq_f32_e32 v233, v233
	s_and_saveexec_b64 s[22:23], s[20:21]
	s_xor_b32 s11, s11, 0x100
	v_lshl_add_u32 v226, s11, 2, v152
	ds_write_b32 v226, v233
	s_or_b64 exec, exec, s[22:23]
	s_mov_b64 s[20:21], -1
	s_cmp_eq_u32 s82, 21
	v_add_u32_e32 v234, 0x10000, v150
	v_add_u32_e32 v235, 0x14000, v150
	ds_read_b128 v[98:101], v234
	ds_read_b128 v[156:159], v234 offset:1024
	ds_read_b128 v[160:163], v234 offset:2048
	ds_read_b128 v[164:167], v234 offset:3072
	ds_read_b128 v[168:171], v235
	ds_read_b128 v[172:175], v235 offset:1024
	ds_read_b128 v[176:179], v235 offset:2048
	ds_read_b128 v[180:183], v235 offset:3072
	ds_read_b128 v[184:187], v154
	ds_read_b128 v[188:191], v154 offset:1024
	ds_read_b128 v[192:195], v154 offset:2048
	ds_read_b128 v[196:199], v154 offset:3072
	ds_read_b128 v[200:203], v154 offset:4096
	ds_read_b128 v[204:207], v154 offset:5120
	ds_read_b128 v[208:211], v154 offset:6144
	ds_read_b128 v[214:217], v154 offset:7168
	v_mul_f32_e32 v230, 0xbfb8aa3b, v240
	v_mul_f32_e32 v243, v240, v240
	v_rcp_f32_e32 v243, v243
	v_exp_f32_e32 v62, v62
	v_mul_f32_e32 v38, v46, v38
	v_exp_f32_e32 v63, v63
	v_mul_f32_e32 v39, v47, v39
	v_exp_f32_e32 v64, v64
	v_mul_f32_e32 v40, v48, v40
	v_exp_f32_e32 v65, v65
	v_mul_f32_e32 v41, v49, v41
	v_exp_f32_e32 v58, v58
	v_mul_f32_e32 v34, v42, v34
	v_exp_f32_e32 v59, v59
	v_mul_f32_e32 v35, v43, v35
	v_exp_f32_e32 v60, v60
	v_mul_f32_e32 v36, v44, v36
	v_exp_f32_e32 v61, v61
	v_mul_f32_e32 v37, v45, v37
	v_fma_f32 v62, v62, v231, v231
	v_mul_f32_e32 v46, v230, v46
	v_fma_f32 v63, v63, v231, v231
	v_rcp_f32_e32 v62, v62
	v_mul_f32_e32 v47, v230, v47
	v_fma_f32 v64, v64, v231, v231
	v_rcp_f32_e32 v63, v63
	v_mul_f32_e32 v48, v230, v48
	v_fma_f32 v65, v65, v231, v231
	v_rcp_f32_e32 v64, v64
	v_mul_f32_e32 v49, v230, v49
	v_fma_f32 v58, v58, v231, v231
	v_rcp_f32_e32 v65, v65
	v_mul_f32_e32 v42, v230, v42
	v_fma_f32 v59, v59, v231, v231
	v_rcp_f32_e32 v58, v58
	v_mul_f32_e32 v43, v230, v43
	v_fma_f32 v60, v60, v231, v231
	v_rcp_f32_e32 v59, v59
	v_mul_f32_e32 v44, v230, v44
	v_fma_f32 v61, v61, v231, v231
	v_rcp_f32_e32 v60, v60
	v_mul_f32_e32 v45, v230, v45
	v_rcp_f32_e32 v61, v61
	v_mul_f32_e32 v54, v54, v62
	v_mul_f32_e32 v55, v55, v63
	v_mul_f32_e32 v56, v56, v64
; __device__ __forceinline__ unsigned cvt_pk_bf16(float lo, float hi) { unsigned r; asm volatile("v_cvt_pk_bf16_f32 %0, %1, %2" : "=v"(r) : "v"(lo), "v"(hi)); return r; }
; #define LAS __attribute__((address_space(3)))
; __device__ __forceinline__ float sigmoid_f(float x) { return __builtin_amdgcn_rcpf(1.0f + __builtin_amdgcn_exp2f(-1.4426950408889634f * x)); }
; __device__ __forceinline__ float rstd4(const f32x4 q) { return __builtin_amdgcn_rsqf(((q[0] + q[1]) + (q[2] + q[3])) * (1.0f / DM) + EPS); }
;     __device__ __forceinline__ void operator()(const f32x4 (&acc)[2][2][4][2], const pg8::Unit& u, int wr, int wc, int fr, int fq, LAS unsigned char* lds, int wid, int lane, const pg8::Unit& nxt, bool has_next, int ui) const {
;     ...
; #pragma unroll
;         for (int ai = 0; ai < 2; ++ai) {
; #pragma unroll
;             for (int m = 0; m < 4; ++m) {
;                 const int row = row0 + ai * 128 + m * 16; const float r_ = R[wr * 64 + fr + ai * 128 + m * 16];
;                 const f32x4 g0 = acc[ai][0][m][0] * r_, g1 = acc[ai][0][m][1] * r_, u0 = acc[ai][1][m][0] * r_, u1 = acc[ai][1][m][1] * r_;
;                 v4u w;
;                 w.x = cvt_pk_bf16(g0[0] * sigmoid_f(g0[0]) * u0[0], g0[1] * sigmoid_f(g0[1]) * u0[1]); w.y = cvt_pk_bf16(g0[2] * sigmoid_f(g0[2]) * u0[2], g0[3] * sigmoid_f(g0[3]) * u0[3]);
;                 w.z = cvt_pk_bf16(g1[0] * sigmoid_f(g1[0]) * u1[0], g1[1] * sigmoid_f(g1[1]) * u1[1]); w.w = cvt_pk_bf16(g1[2] * sigmoid_f(g1[2]) * u1[2], g1[3] * sigmoid_f(g1[3]) * u1[3]);
;                 *(v4u*)(ACT + (size_t)row * FF + col) = w;
;             }
;             if (ai == 0) {
;                 __builtin_amdgcn_sched_barrier(0);
;                 float rn = rstd4(qn); asm volatile("" : "+v"(rn));
;                 if (pre) ((LAS float*)(lds + RS_OFF))[((ui + 1) & 1) * 256 + tid] = rn;
;                 __builtin_amdgcn_sched_barrier(0);
;             }
	v_mul_f32_e32 v57, v57, v65
	v_mul_f32_e32 v50, v50, v58
	v_mul_f32_e32 v51, v51, v59
	v_mul_f32_e32 v52, v52, v60
	v_mul_f32_e32 v53, v53, v61
	v_cvt_pk_bf16_f32 v54, v54, v55
	v_cvt_pk_bf16_f32 v55, v56, v57
	v_cvt_pk_bf16_f32 v56, v50, v51
	v_cvt_pk_bf16_f32 v57, v52, v53
	v_or_b32_e32 v226, 0x80, v236
	v_mad_i64_i32 v[228:229], s[12:13], v226, s55, v[224:225]
	global_store_dwordx4 v[228:229], v[54:57], off
	v_mul_f32_e32 v230, 0xbfb8aa3b, v241
	v_mul_f32_e32 v231, v241, v241
	v_rcp_f32_e32 v231, v231
	v_exp_f32_e32 v46, v46
	v_mul_f32_e32 v22, v30, v22
	v_exp_f32_e32 v47, v47
	v_mul_f32_e32 v23, v31, v23
	v_exp_f32_e32 v48, v48
	v_mul_f32_e32 v24, v32, v24
	v_exp_f32_e32 v49, v49
	v_mul_f32_e32 v25, v33, v25
	v_exp_f32_e32 v42, v42
	v_mul_f32_e32 v18, v26, v18
	v_exp_f32_e32 v43, v43
	v_mul_f32_e32 v19, v27, v19
	v_exp_f32_e32 v44, v44
	v_mul_f32_e32 v20, v28, v20
	v_exp_f32_e32 v45, v45
	v_mul_f32_e32 v21, v29, v21
	v_fma_f32 v46, v46, v243, v243
	v_mul_f32_e32 v30, v230, v30
	v_fma_f32 v47, v47, v243, v243
	v_rcp_f32_e32 v46, v46
	v_mul_f32_e32 v31, v230, v31
	v_fma_f32 v48, v48, v243, v243
	v_rcp_f32_e32 v47, v47
	v_mul_f32_e32 v32, v230, v32
	v_fma_f32 v49, v49, v243, v243
	v_rcp_f32_e32 v48, v48
	v_mul_f32_e32 v33, v230, v33
	v_fma_f32 v42, v42, v243, v243
	v_rcp_f32_e32 v49, v49
	v_mul_f32_e32 v26, v230, v26
	v_fma_f32 v43, v43, v243, v243
	v_rcp_f32_e32 v42, v42
	v_mul_f32_e32 v27, v230, v27
	v_fma_f32 v44, v44, v243, v243
	v_rcp_f32_e32 v43, v43
	v_mul_f32_e32 v28, v230, v28
	v_fma_f32 v45, v45, v243, v243
	v_rcp_f32_e32 v44, v44
	v_mul_f32_e32 v29, v230, v29
	v_rcp_f32_e32 v45, v45
	v_mul_f32_e32 v38, v38, v46
	v_mul_f32_e32 v39, v39, v47
	v_mul_f32_e32 v40, v40, v48
	v_mul_f32_e32 v41, v41, v49
	v_mul_f32_e32 v34, v34, v42
	v_mul_f32_e32 v35, v35, v43
	v_mul_f32_e32 v36, v36, v44
	v_mul_f32_e32 v37, v37, v45
	v_cvt_pk_bf16_f32 v38, v38, v39
	v_cvt_pk_bf16_f32 v39, v40, v41
	v_cvt_pk_bf16_f32 v40, v34, v35
	v_cvt_pk_bf16_f32 v41, v36, v37
	v_or_b32_e32 v226, 0x90, v236
	v_mad_i64_i32 v[228:229], s[12:13], v226, s55, v[224:225]
	global_store_dwordx4 v[228:229], v[38:41], off
	v_mul_f32_e32 v230, 0xbfb8aa3b, v242
	v_mul_f32_e32 v243, v242, v242
	v_rcp_f32_e32 v243, v243
	v_exp_f32_e32 v30, v30
	v_mul_f32_e32 v6, v14, v6
	v_exp_f32_e32 v31, v31
	v_mul_f32_e32 v7, v15, v7
	v_exp_f32_e32 v32, v32
	v_mul_f32_e32 v8, v16, v8
	v_exp_f32_e32 v33, v33
	v_mul_f32_e32 v9, v17, v9
	v_exp_f32_e32 v26, v26
	v_mul_f32_e32 v2, v10, v2
	v_exp_f32_e32 v27, v27
	v_mul_f32_e32 v3, v11, v3
	v_exp_f32_e32 v28, v28
	v_mul_f32_e32 v4, v12, v4
	v_exp_f32_e32 v29, v29
	v_mul_f32_e32 v5, v13, v5
	v_fma_f32 v30, v30, v231, v231
	v_mul_f32_e32 v14, v230, v14
	v_fma_f32 v31, v31, v231, v231
	v_rcp_f32_e32 v30, v30
	v_mul_f32_e32 v15, v230, v15
	v_fma_f32 v32, v32, v231, v231
	v_rcp_f32_e32 v31, v31
	v_mul_f32_e32 v16, v230, v16
	v_fma_f32 v33, v33, v231, v231
	v_rcp_f32_e32 v32, v32
	v_mul_f32_e32 v17, v230, v17
	v_fma_f32 v26, v26, v231, v231
	v_rcp_f32_e32 v33, v33
	v_mul_f32_e32 v10, v230, v10
	v_fma_f32 v27, v27, v231, v231
	v_rcp_f32_e32 v26, v26
	v_mul_f32_e32 v11, v230, v11
	v_fma_f32 v28, v28, v231, v231
	v_rcp_f32_e32 v27, v27
	v_mul_f32_e32 v12, v230, v12
	v_fma_f32 v29, v29, v231, v231
	v_rcp_f32_e32 v28, v28
	v_mul_f32_e32 v13, v230, v13
	v_rcp_f32_e32 v29, v29
	v_mul_f32_e32 v22, v22, v30
	v_mul_f32_e32 v23, v23, v31
	v_mul_f32_e32 v24, v24, v32
	v_mul_f32_e32 v25, v25, v33
	v_mul_f32_e32 v18, v18, v26
	v_mul_f32_e32 v19, v19, v27
	v_mul_f32_e32 v20, v20, v28
	v_mul_f32_e32 v21, v21, v29
	v_cvt_pk_bf16_f32 v22, v22, v23
	v_cvt_pk_bf16_f32 v23, v24, v25
	v_cvt_pk_bf16_f32 v24, v18, v19
	v_cvt_pk_bf16_f32 v25, v20, v21
	v_or_b32_e32 v226, 0xa0, v236
	v_mad_i64_i32 v[228:229], s[12:13], v226, s55, v[224:225]
	global_store_dwordx4 v[228:229], v[22:25], off
	v_exp_f32_e32 v14, v14
	v_exp_f32_e32 v15, v15
	v_exp_f32_e32 v16, v16
	v_exp_f32_e32 v17, v17
	v_exp_f32_e32 v10, v10
	v_exp_f32_e32 v11, v11
	v_exp_f32_e32 v12, v12
	v_exp_f32_e32 v13, v13
	v_fma_f32 v14, v14, v243, v243
	v_fma_f32 v15, v15, v243, v243
	v_rcp_f32_e32 v14, v14
	v_fma_f32 v16, v16, v243, v243
	v_rcp_f32_e32 v15, v15
	v_fma_f32 v17, v17, v243, v243
	v_rcp_f32_e32 v16, v16
	v_fma_f32 v10, v10, v243, v243
	v_rcp_f32_e32 v17, v17
	v_fma_f32 v11, v11, v243, v243
	v_rcp_f32_e32 v10, v10
	v_fma_f32 v12, v12, v243, v243
	v_rcp_f32_e32 v11, v11
	v_fma_f32 v13, v13, v243, v243
	v_rcp_f32_e32 v12, v12
	v_rcp_f32_e32 v13, v13
	v_mul_f32_e32 v6, v6, v14
	v_mul_f32_e32 v7, v7, v15
	v_mul_f32_e32 v8, v8, v16
	v_mul_f32_e32 v9, v9, v17
	v_mul_f32_e32 v2, v2, v10
	v_mul_f32_e32 v3, v3, v11
	v_mul_f32_e32 v4, v4, v12
	v_mul_f32_e32 v5, v5, v13
	v_cvt_pk_bf16_f32 v6, v6, v7
	v_cvt_pk_bf16_f32 v7, v8, v9
	v_cvt_pk_bf16_f32 v8, v2, v3
	v_cvt_pk_bf16_f32 v9, v4, v5
	v_or_b32_e32 v226, 0xb0, v236
	v_mad_i64_i32 v[228:229], s[12:13], v226, s55, v[224:225]
	global_store_dwordx4 v[228:229], v[6:9], off
	s_cbranch_scc1 .LBB0_574
	s_andn2_b64 vcc, exec, s[6:7]
	s_cbranch_vccnz .LBB0_573
	s_barrier
	s_branch .LBB0_573
